# plus: weight-conversion tile ranges rebalanced between GEMM tails (less in the first-down and layer-1 GU tails)
# speedup vs baseline: 1.0271x; 1.0067x over previous
; __device__ __forceinline__ unsigned cvt_pk_bf16(float lo, float hi) { unsigned r; asm("v_cvt_pk_bf16_f32 %0, %1, %2" : "=v"(r) : "v"(lo), "v"(hi)); return r; }
; __device__ __forceinline__ float bf2f(unsigned b) { return __uint_as_float(b << 16); }
; __device__ __forceinline__ void r1s_phase(KP p, int G, int bid, int wv) {
;     ...
;     const bf16_t* pr = (const bf16_t*)(ws + WS_PR); bf16_t* Y = (bf16_t*)(ws + WS_Y); const float* wc = p->in[16];
;     for (int e = bid * 512 + tid; e < MLAT * 128; e += G * 512) {
;         const int row = e >> 7, c8 = (e & 127) * 8, t = row & (SEQ - 1);
;         const bf16_t* rp = pr + (size_t)row * 4096;
;         const u32x4 bg = *(const u32x4*)(rp + 1024 + c8);
;         const u32x4 c1 = *(const u32x4*)(rp + 2048 + c8), u1 = *(const u32x4*)(rp + 3072 + c8);
;         u32x4 c0 = {0, 0, 0, 0}, u0 = {0, 0, 0, 0}, c2 = {0, 0, 0, 0}, u2 = {0, 0, 0, 0};
;         if (t > 0) { c0 = *(const u32x4*)(rp - 4096 + 2048 + c8); u0 = *(const u32x4*)(rp - 4096 + 3072 + c8); }
;         if (t < SEQ - 1) { c2 = *(const u32x4*)(rp + 4096 + 2048 + c8); u2 = *(const u32x4*)(rp + 4096 + 3072 + c8); }
;         float o[8];
; #pragma unroll
;         for (int i = 0; i < 4; ++i) {
; #pragma unroll
;             for (int hh = 0; hh < 2; ++hh) {
;                 const int sh = hh * 16, ch = c8 + 2 * i + hh;
;                 const float m0 = bf2f((c0[i] >> sh) & 0xffffu) * bf2f((u0[i] >> sh) & 0xffffu);
;                 const float m1 = bf2f((c1[i] >> sh) & 0xffffu) * bf2f((u1[i] >> sh) & 0xffffu);
;                 const float m2 = bf2f((c2[i] >> sh) & 0xffffu) * bf2f((u2[i] >> sh) & 0xffffu);
;                 o[2 * i + hh] = bf2f((bg[i] >> sh) & 0xffffu) * (m0 * wc[ch] + m1 * wc[1024 + ch] + m2 * wc[2048 + ch]);
;             }
;         }
;         u32x4 w; w.x = cvt_pk_bf16(o[0], o[1]); w.y = cvt_pk_bf16(o[2], o[3]); w.z = cvt_pk_bf16(o[4], o[5]); w.w = cvt_pk_bf16(o[6], o[7]);
;         *(u32x4*)(Y + (size_t)row * DM + 1024 + c8) = w;
;     }
.LBB0_114:
	v_add_u32_e32 v44, s60, v93
	s_mov_b32 s0, 0x100000
	v_cmp_gt_i32_e32 vcc, s0, v44
	s_mov_b64 s[2:3], exec
	v_readlane_b32 s36, v253, 39
	v_readlane_b32 s12, v254, 35
	s_and_b64 s[0:1], s[2:3], vcc
	v_readlane_b32 s37, v253, 40
	s_mov_b64 s[10:11], 0x2000
	v_readlane_b32 s13, v254, 36
	v_mov_b32_e32 v247, v252
	s_mov_b64 exec, s[0:1]
	s_cbranch_execz .LBB0_121
	s_load_dwordx2 s[4:5], s[78:79], 0x80
	s_mov_b32 s20, s33
.Lgc_loop:
	v_lshrrev_b32_e32 v118, 7, v93
	v_and_b32_e32 v119, 0x7f, v93
	v_lshlrev_b32_e32 v86, 4, v119
	v_lshlrev_b32_e32 v87, 5, v119
	v_readfirstlane_b32 s8, v118
	s_lshl_b32 s9, s20, 5
	s_lshl_b32 s8, s8, 3
	s_add_i32 s8, s8, s9
	s_and_b32 s9, s8, 0x7ff
	s_lshl_b32 s10, s8, 13
	s_add_u32 s16, s80, s10
	s_addc_u32 s17, s81, 0
	s_add_u32 s16, s16, 0x242b5000
	s_addc_u32 s17, s17, 0
	s_lshl_b32 s10, s8, 12
	s_add_u32 s18, s80, s10
	s_addc_u32 s19, s81, 0
	s_add_u32 s18, s18, 0x2eab4800
	s_addc_u32 s19, s19, 0
	s_waitcnt lgkmcnt(0)
	global_load_dwordx4 v[2:5], v87, s[4:5]
	global_load_dwordx4 v[6:9], v87, s[4:5] offset:16
	s_add_u32 s10, s4, 0x1000
	s_addc_u32 s11, s5, 0
	global_load_dwordx4 v[10:13], v87, s[10:11]
	global_load_dwordx4 v[14:17], v87, s[10:11] offset:16
	s_add_u32 s10, s4, 0x2000
	s_addc_u32 s11, s5, 0
	global_load_dwordx4 v[18:21], v87, s[10:11]
	global_load_dwordx4 v[22:25], v87, s[10:11] offset:16
	s_sub_u32 s10, s16, 0x2000
	s_subb_u32 s11, s17, 0
	global_load_dwordx4 v[26:29], v86, s[10:11]
	global_load_dwordx4 v[30:33], v86, s[10:11] offset:2048
	s_add_u32 s10, s16, 0x0
	s_addc_u32 s11, s17, 0
	global_load_dwordx4 v[34:37], v86, s[10:11]
	global_load_dwordx4 v[38:41], v86, s[10:11] offset:2048
	global_load_dwordx4 v[62:65], v86, s[10:11] offset:-2048
	s_add_u32 s10, s16, 0x2000
	s_addc_u32 s11, s17, 0
	global_load_dwordx4 v[42:45], v86, s[10:11]
	global_load_dwordx4 v[46:49], v86, s[10:11] offset:2048
	global_load_dwordx4 v[66:69], v86, s[10:11] offset:-2048
	s_add_u32 s10, s16, 0x4000
	s_addc_u32 s11, s17, 0
	global_load_dwordx4 v[54:57], v86, s[10:11]
	global_load_dwordx4 v[58:61], v86, s[10:11] offset:2048
	global_load_dwordx4 v[70:73], v86, s[10:11] offset:-2048
	s_waitcnt vmcnt(11)
	s_cmp_eq_u32 s9, 0
	s_waitcnt vmcnt(9)
	s_cbranch_scc1 .Lgc_zero_1
	v_lshlrev_b32_e32 v118, 16, v26
	v_lshlrev_b32_e32 v119, 16, v30
	v_mul_f32_e32 v94, v118, v119
	v_and_b32_e32 v26, 0xffff0000, v26
	v_and_b32_e32 v30, 0xffff0000, v30
	v_mul_f32_e32 v95, v26, v30
	v_lshlrev_b32_e32 v118, 16, v27
	v_lshlrev_b32_e32 v119, 16, v31
	v_mul_f32_e32 v96, v118, v119
	v_and_b32_e32 v27, 0xffff0000, v27
	v_and_b32_e32 v31, 0xffff0000, v31
	v_mul_f32_e32 v97, v27, v31
	v_lshlrev_b32_e32 v118, 16, v28
	v_lshlrev_b32_e32 v119, 16, v32
	v_mul_f32_e32 v98, v118, v119
	v_and_b32_e32 v28, 0xffff0000, v28
	v_and_b32_e32 v32, 0xffff0000, v32
	v_mul_f32_e32 v99, v28, v32
	v_lshlrev_b32_e32 v118, 16, v29
	v_lshlrev_b32_e32 v119, 16, v33
	v_mul_f32_e32 v100, v118, v119
	v_and_b32_e32 v29, 0xffff0000, v29
	v_and_b32_e32 v33, 0xffff0000, v33
	v_mul_f32_e32 v101, v29, v33
	s_branch .Lgc_done_1

; __device__ __forceinline__ unsigned cvt_pk_bf16(float lo, float hi) { unsigned r; asm("v_cvt_pk_bf16_f32 %0, %1, %2" : "=v"(r) : "v"(lo), "v"(hi)); return r; }
; __device__ __forceinline__ float bf2f(unsigned b) { return __uint_as_float(b << 16); }
; __device__ __forceinline__ void r1s_phase(KP p, int G, int bid, int wv) {
;     ...
;         float o[8];
; #pragma unroll
;         for (int i = 0; i < 4; ++i) {
; #pragma unroll
;             for (int hh = 0; hh < 2; ++hh) {
;                 const int sh = hh * 16, ch = c8 + 2 * i + hh;
;                 const float m0 = bf2f((c0[i] >> sh) & 0xffffu) * bf2f((u0[i] >> sh) & 0xffffu);
;                 const float m1 = bf2f((c1[i] >> sh) & 0xffffu) * bf2f((u1[i] >> sh) & 0xffffu);
;                 const float m2 = bf2f((c2[i] >> sh) & 0xffffu) * bf2f((u2[i] >> sh) & 0xffffu);
;                 o[2 * i + hh] = bf2f((bg[i] >> sh) & 0xffffu) * (m0 * wc[ch] + m1 * wc[1024 + ch] + m2 * wc[2048 + ch]);
;             }
;         }
;         u32x4 w; w.x = cvt_pk_bf16(o[0], o[1]); w.y = cvt_pk_bf16(o[2], o[3]); w.z = cvt_pk_bf16(o[4], o[5]); w.w = cvt_pk_bf16(o[6], o[7]);
;         *(u32x4*)(Y + (size_t)row * DM + 1024 + c8) = w;
;     }
.Lgc_done_2:
	s_waitcnt vmcnt(5)
	v_mul_f32_e32 v78, v102, v2
	v_mul_f32_e32 v118, v94, v18
	v_fma_f32 v78, v110, v10, v78
	v_add_f32_e32 v78, v78, v118
	v_lshlrev_b32_e32 v119, 16, v74
	v_mul_f32_e32 v78, v78, v119
	v_mul_f32_e32 v79, v103, v3
	v_mul_f32_e32 v118, v95, v19
	v_fma_f32 v79, v111, v11, v79
	v_add_f32_e32 v79, v79, v118
	v_and_b32_e32 v119, 0xffff0000, v74
	v_mul_f32_e32 v79, v79, v119
	v_mul_f32_e32 v80, v104, v4
	v_mul_f32_e32 v118, v96, v20
	v_fma_f32 v80, v112, v12, v80
	v_add_f32_e32 v80, v80, v118
	v_lshlrev_b32_e32 v119, 16, v75
	v_mul_f32_e32 v80, v80, v119
	v_mul_f32_e32 v81, v105, v5
	v_mul_f32_e32 v118, v97, v21
	v_fma_f32 v81, v113, v13, v81
	v_add_f32_e32 v81, v81, v118
	v_and_b32_e32 v119, 0xffff0000, v75
	v_mul_f32_e32 v81, v81, v119
	v_mul_f32_e32 v82, v106, v6
	v_mul_f32_e32 v118, v98, v22
	v_fma_f32 v82, v114, v14, v82
	v_add_f32_e32 v82, v82, v118
	v_lshlrev_b32_e32 v119, 16, v76
	v_mul_f32_e32 v82, v82, v119
	v_mul_f32_e32 v83, v107, v7
	v_mul_f32_e32 v118, v99, v23
	v_fma_f32 v83, v115, v15, v83
	v_add_f32_e32 v83, v83, v118
	v_and_b32_e32 v119, 0xffff0000, v76
	v_mul_f32_e32 v83, v83, v119
	v_mul_f32_e32 v84, v108, v8
	v_mul_f32_e32 v118, v100, v24
	v_fma_f32 v84, v116, v16, v84
	v_add_f32_e32 v84, v84, v118
	v_lshlrev_b32_e32 v119, 16, v77
	v_mul_f32_e32 v84, v84, v119
	v_mul_f32_e32 v85, v109, v9
	v_mul_f32_e32 v118, v101, v25
	v_fma_f32 v85, v117, v17, v85
	v_add_f32_e32 v85, v85, v118
	v_and_b32_e32 v119, 0xffff0000, v77
	v_mul_f32_e32 v85, v85, v119
	v_cvt_pk_bf16_f32 v120, v78, v79
	v_cvt_pk_bf16_f32 v121, v80, v81
	v_cvt_pk_bf16_f32 v122, v82, v83
	v_cvt_pk_bf16_f32 v123, v84, v85
	s_add_u32 s10, s18, 0x7000
	s_addc_u32 s11, s19, 0
	global_store_dwordx4 v86, v[120:123], s[10:11]
	s_add_i32 s20, s20, s42
	s_cmpk_lt_i32 s20, 0x100
	s_cbranch_scc1 .Lgc_loop

; __device__ __forceinline__ void conv_tiles(KP p, LAS unsigned char* lds, int which, int idx, int stride, int wv) {
;     ...
;     switch (which) {
;         case 0: R = ConvRanges{0, 2816, 0, 0, 0, 0}; break;
;         case 1: R = ConvRanges{11264, 12672, 2816, 5120, 0, 0}; break;
;         case 2: R = ConvRanges{16896, 18688, 5120, 6528, 0, 0}; break;
;         case 3: R = ConvRanges{18688, 19328, 6528, 7424, 0, 0}; break;
;         case 4: R = ConvRanges{12672, 14080, 7424, 8448, 0, 0}; break;
;         case 5: R = ConvRanges{14080, 15488, 8448, 11264, 0, 0}; break;
;         default: R = ConvRanges{15488, 16896, 0, 0, 0, 0}; break;
;     }
.LBB0_606:
	s_andn2_b64 vcc, exec, s[0:1]
	s_cbranch_vccnz .LBB0_860
	s_movk_i32 s12, 0x3700
	s_movk_i32 s10, 0x3c80
	s_movk_i32 s11, 0x2500
	s_movk_i32 s27, 0x2c00
	s_mov_b64 s[0:1], 0

; __device__ __forceinline__ void conv_tiles(KP p, LAS unsigned char* lds, int which, int idx, int stride, int wv) {
;     ...
;     switch (which) {
;         case 0: R = ConvRanges{0, 2816, 0, 0, 0, 0}; break;
;         case 1: R = ConvRanges{11264, 12672, 2816, 5120, 0, 0}; break;
;         case 2: R = ConvRanges{16896, 18688, 5120, 6528, 0, 0}; break;
;         case 3: R = ConvRanges{18688, 19328, 6528, 7424, 0, 0}; break;
;         case 4: R = ConvRanges{12672, 14080, 7424, 8448, 0, 0}; break;
;         case 5: R = ConvRanges{14080, 15488, 8448, 11264, 0, 0}; break;
;         default: R = ConvRanges{15488, 16896, 0, 0, 0, 0}; break;
;     }
.LBB0_609:
	s_movk_i32 s12, 0x3180
	s_movk_i32 s10, 0x3700
	s_movk_i32 s11, 0x1f00
	s_movk_i32 s27, 0x2500

; __device__ __forceinline__ void conv_tiles(KP p, LAS unsigned char* lds, int which, int idx, int stride, int wv) {
;     ...
;     switch (which) {
;         case 0: R = ConvRanges{0, 2816, 0, 0, 0, 0}; break;
;         case 1: R = ConvRanges{11264, 12672, 2816, 5120, 0, 0}; break;
;         case 2: R = ConvRanges{16896, 18688, 5120, 6528, 0, 0}; break;
;         case 3: R = ConvRanges{18688, 19328, 6528, 7424, 0, 0}; break;
;         case 4: R = ConvRanges{12672, 14080, 7424, 8448, 0, 0}; break;
;         case 5: R = ConvRanges{14080, 15488, 8448, 11264, 0, 0}; break;
;         default: R = ConvRanges{15488, 16896, 0, 0, 0, 0}; break;
;     }
.LBB0_611:
	s_andn2_b64 vcc, exec, s[0:1]
	s_cbranch_vccnz .LBB0_613
	s_movk_i32 s12, 0x4900
	s_movk_i32 s10, 0x4b80
	s_movk_i32 s11, 0x1980
	s_movk_i32 s27, 0x1f00

; __device__ __forceinline__ void conv_tiles(KP p, LAS unsigned char* lds, int which, int idx, int stride, int wv) {
;     ...
;     switch (which) {
;         case 0: R = ConvRanges{0, 2816, 0, 0, 0, 0}; break;
;         case 1: R = ConvRanges{11264, 12672, 2816, 5120, 0, 0}; break;
;         case 2: R = ConvRanges{16896, 18688, 5120, 6528, 0, 0}; break;
;         case 3: R = ConvRanges{18688, 19328, 6528, 7424, 0, 0}; break;
;         case 4: R = ConvRanges{12672, 14080, 7424, 8448, 0, 0}; break;
;         case 5: R = ConvRanges{14080, 15488, 8448, 11264, 0, 0}; break;
;         default: R = ConvRanges{15488, 16896, 0, 0, 0, 0}; break;
;     }
.LBB0_618:
	s_andn2_b64 vcc, exec, s[0:1]
	s_cbranch_vccnz .LBB0_621
	s_movk_i32 s12, 0x2c00
	s_movk_i32 s10, 0x3180
	s_movk_i32 s11, 0xb00
	s_movk_i32 s13, 0x1700
	s_branch .LBB0_622

; __device__ __forceinline__ void conv_tiles(KP p, LAS unsigned char* lds, int which, int idx, int stride, int wv) {
;     ...
;     switch (which) {
;         case 0: R = ConvRanges{0, 2816, 0, 0, 0, 0}; break;
;         case 1: R = ConvRanges{11264, 12672, 2816, 5120, 0, 0}; break;
;         case 2: R = ConvRanges{16896, 18688, 5120, 6528, 0, 0}; break;
;         case 3: R = ConvRanges{18688, 19328, 6528, 7424, 0, 0}; break;
;         case 4: R = ConvRanges{12672, 14080, 7424, 8448, 0, 0}; break;
;         case 5: R = ConvRanges{14080, 15488, 8448, 11264, 0, 0}; break;
;         default: R = ConvRanges{15488, 16896, 0, 0, 0, 0}; break;
;     }
.LBB0_621:
	s_movk_i32 s12, 0x4200
	s_movk_i32 s10, 0x4900
	s_movk_i32 s11, 0x1700
	s_movk_i32 s13, 0x1980
